# out-proj epilogue residual/gate loads nt on top of sc1 nt GEMM stores
# baseline (speedup 1.0000x reference)
; #define GCOMPUTE(AS, BS) GCOMPUTE_KS(AS, BS, 0) GCOMPUTE_KS(AS, BS, 1)
; template <int EPI>
; DI void gemm_phase(const P& p, int l, const u16* __restrict__ A, const u16* __restrict__ Bt, int mpx, char* lds) {
;     ...
;   __syncthreads();
;   __builtin_amdgcn_sched_barrier(0);
;   GCOMPUTE(As1, Bs1)
;   __builtin_amdgcn_sched_barrier(0);
;   }
;   __syncthreads();
.Lgemm_out_exit:
	v_mfma_f32_16x16x32_bf16 v[134:137], v[246:249], v[162:165], v[134:137]
	v_mfma_f32_16x16x32_bf16 v[138:141], v[246:249], v[166:169], v[138:141]
	v_mfma_f32_16x16x32_bf16 v[142:145], v[246:249], v[170:173], v[142:145]
	v_mfma_f32_16x16x32_bf16 v[146:149], v[246:249], v[174:177], v[146:149]
	v_mfma_f32_16x16x32_bf16 v[150:153], v[250:253], v[162:165], v[150:153]
	v_mfma_f32_16x16x32_bf16 v[154:157], v[250:253], v[166:169], v[154:157]
	v_mfma_f32_16x16x32_bf16 v[158:161], v[250:253], v[170:173], v[158:161]
	v_mfma_f32_16x16x32_bf16 v[2:5], v[250:253], v[174:177], v[2:5]
	s_barrier
	ds_read_b128 v[162:165], v231
	ds_read_b128 v[166:169], v230
	ds_read_b128 v[170:173], v230 offset:2048
	ds_read_b128 v[174:177], v230 offset:4096
	ds_read_b128 v[178:181], v230 offset:6144
	s_waitcnt lgkmcnt(3)
	v_mfma_f32_16x16x32_bf16 v[6:9], v[162:165], v[166:169], v[6:9]
	s_waitcnt lgkmcnt(2)
	v_mfma_f32_16x16x32_bf16 v[10:13], v[162:165], v[170:173], v[10:13]
	s_waitcnt lgkmcnt(1)
	v_mfma_f32_16x16x32_bf16 v[14:17], v[162:165], v[174:177], v[14:17]
	s_waitcnt lgkmcnt(0)
	v_mfma_f32_16x16x32_bf16 v[22:25], v[162:165], v[178:181], v[22:25]
	ds_read_b128 v[162:165], v231 offset:2048
	s_waitcnt lgkmcnt(0)
	v_mfma_f32_16x16x32_bf16 v[26:29], v[162:165], v[166:169], v[26:29]
	v_mfma_f32_16x16x32_bf16 v[30:33], v[162:165], v[170:173], v[30:33]
	v_mfma_f32_16x16x32_bf16 v[34:37], v[162:165], v[174:177], v[34:37]
	v_mfma_f32_16x16x32_bf16 v[38:41], v[162:165], v[178:181], v[38:41]
	ds_read_b128 v[162:165], v231 offset:4096
	s_waitcnt lgkmcnt(0)
	v_mfma_f32_16x16x32_bf16 v[42:45], v[162:165], v[166:169], v[42:45]
	v_mfma_f32_16x16x32_bf16 v[46:49], v[162:165], v[170:173], v[46:49]
	v_mfma_f32_16x16x32_bf16 v[50:53], v[162:165], v[174:177], v[50:53]
	v_mfma_f32_16x16x32_bf16 v[54:57], v[162:165], v[178:181], v[54:57]
	ds_read_b128 v[162:165], v231 offset:6144
	s_waitcnt lgkmcnt(0)
	v_mfma_f32_16x16x32_bf16 v[58:61], v[162:165], v[166:169], v[58:61]
	v_mfma_f32_16x16x32_bf16 v[62:65], v[162:165], v[170:173], v[62:65]
	v_mfma_f32_16x16x32_bf16 v[66:69], v[162:165], v[174:177], v[66:69]
	v_mfma_f32_16x16x32_bf16 v[162:165], v[162:165], v[178:181], v[70:73]
	s_nop 2
	ds_read_b128 v[70:73], v231 offset:8192
	s_waitcnt lgkmcnt(0)
	v_mfma_f32_16x16x32_bf16 v[182:185], v[70:73], v[166:169], v[74:77]
	s_nop 2
	ds_read_b128 v[74:77], v233
	v_mfma_f32_16x16x32_bf16 v[186:189], v[70:73], v[170:173], v[78:81]
	v_mfma_f32_16x16x32_bf16 v[190:193], v[70:73], v[174:177], v[82:85]
	v_mfma_f32_16x16x32_bf16 v[212:215], v[70:73], v[178:181], v[114:117]
	ds_read_b128 v[70:73], v231 offset:10240
	s_waitcnt lgkmcnt(0)
	v_mfma_f32_16x16x32_bf16 v[216:219], v[70:73], v[166:169], v[118:121]
	v_mfma_f32_16x16x32_bf16 v[220:223], v[70:73], v[170:173], v[122:125]
	v_mfma_f32_16x16x32_bf16 v[234:237], v[70:73], v[174:177], v[126:129]
	v_mfma_f32_16x16x32_bf16 v[238:241], v[70:73], v[178:181], v[130:133]
	ds_read_b128 v[70:73], v231 offset:12288
	s_waitcnt lgkmcnt(0)
	v_mfma_f32_16x16x32_bf16 v[242:245], v[70:73], v[166:169], v[134:137]
	v_mfma_f32_16x16x32_bf16 v[246:249], v[70:73], v[170:173], v[138:141]
	v_mfma_f32_16x16x32_bf16 v[250:253], v[70:73], v[174:177], v[142:145]
	v_mfma_f32_16x16x32_bf16 v[208:211], v[70:73], v[178:181], v[146:149]
	ds_read_b128 v[70:73], v231 offset:14336
	s_waitcnt lgkmcnt(0)
	v_mfma_f32_16x16x32_bf16 v[178:181], v[70:73], v[178:181], v[2:5]
	s_nop 2
	ds_read_b128 v[2:5], v232
	s_waitcnt lgkmcnt(0)
	v_mfma_f32_16x16x32_bf16 v[146:149], v[74:77], v[2:5], v[6:9]
	s_nop 2
	ds_read_b128 v[6:9], v232 offset:2048
	v_mfma_f32_16x16x32_bf16 v[170:173], v[70:73], v[170:173], v[154:157]
	s_waitcnt lgkmcnt(0)
	v_mfma_f32_16x16x32_bf16 v[154:157], v[74:77], v[6:9], v[10:13]
	s_nop 2
	ds_read_b128 v[10:13], v232 offset:4096
	v_mfma_f32_16x16x32_bf16 v[166:169], v[70:73], v[166:169], v[150:153]
	s_waitcnt lgkmcnt(0)
	v_mfma_f32_16x16x32_bf16 v[150:153], v[74:77], v[10:13], v[14:17]
	s_nop 2
	ds_read_b128 v[14:17], v232 offset:6144
	v_mfma_f32_16x16x32_bf16 v[174:177], v[70:73], v[174:177], v[158:161]
	s_waitcnt lgkmcnt(0)
	v_mfma_f32_16x16x32_bf16 v[158:161], v[74:77], v[14:17], v[22:25]
	s_nop 2
	ds_read_b128 v[22:25], v233 offset:2048
	s_waitcnt lgkmcnt(0)
	v_mfma_f32_16x16x32_bf16 v[138:141], v[22:25], v[2:5], v[26:29]
	s_nop 2
	ds_read_b128 v[26:29], v233 offset:12288
	v_mfma_f32_16x16x32_bf16 v[142:145], v[22:25], v[6:9], v[30:33]
	v_mfma_f32_16x16x32_bf16 v[130:133], v[22:25], v[10:13], v[34:37]
	v_mfma_f32_16x16x32_bf16 v[134:137], v[22:25], v[14:17], v[38:41]
	ds_read_b128 v[22:25], v233 offset:4096
	s_waitcnt lgkmcnt(0)
	v_mfma_f32_16x16x32_bf16 v[122:125], v[22:25], v[2:5], v[42:45]
	v_mfma_f32_16x16x32_bf16 v[126:129], v[22:25], v[6:9], v[46:49]
	v_mfma_f32_16x16x32_bf16 v[114:117], v[22:25], v[10:13], v[50:53]
	v_mfma_f32_16x16x32_bf16 v[118:121], v[22:25], v[14:17], v[54:57]
	ds_read_b128 v[22:25], v233 offset:6144
	s_waitcnt lgkmcnt(0)
	v_mfma_f32_16x16x32_bf16 v[78:81], v[22:25], v[2:5], v[58:61]
	v_mfma_f32_16x16x32_bf16 v[82:85], v[22:25], v[6:9], v[62:65]
	v_mfma_f32_16x16x32_bf16 v[70:73], v[22:25], v[10:13], v[66:69]
	v_mfma_f32_16x16x32_bf16 v[74:77], v[22:25], v[14:17], v[162:165]
	ds_read_b128 v[22:25], v233 offset:8192
	s_nop 1
	ds_read_b128 v[162:165], v233 offset:14336
	s_waitcnt lgkmcnt(1)
	v_mfma_f32_16x16x32_bf16 v[62:65], v[22:25], v[2:5], v[182:185]
	v_mfma_f32_16x16x32_bf16 v[66:69], v[22:25], v[6:9], v[186:189]
	v_mfma_f32_16x16x32_bf16 v[54:57], v[22:25], v[10:13], v[190:193]
	v_mfma_f32_16x16x32_bf16 v[58:61], v[22:25], v[14:17], v[212:215]
	ds_read_b128 v[22:25], v233 offset:10240
	s_waitcnt lgkmcnt(0)
	v_mfma_f32_16x16x32_bf16 v[46:49], v[22:25], v[2:5], v[216:219]
	v_mfma_f32_16x16x32_bf16 v[50:53], v[22:25], v[6:9], v[220:223]
	v_mfma_f32_16x16x32_bf16 v[38:41], v[22:25], v[10:13], v[234:237]
	v_mfma_f32_16x16x32_bf16 v[42:45], v[22:25], v[14:17], v[238:241]
	v_mfma_f32_16x16x32_bf16 v[30:33], v[26:29], v[2:5], v[242:245]
	v_mfma_f32_16x16x32_bf16 v[34:37], v[26:29], v[6:9], v[246:249]
	v_mfma_f32_16x16x32_bf16 v[22:25], v[26:29], v[10:13], v[250:253]
	v_mfma_f32_16x16x32_bf16 v[26:29], v[26:29], v[14:17], v[208:211]
	v_mfma_f32_16x16x32_bf16 v[166:169], v[162:165], v[2:5], v[166:169]
	v_mfma_f32_16x16x32_bf16 v[170:173], v[162:165], v[6:9], v[170:173]
	v_mfma_f32_16x16x32_bf16 v[2:5], v[162:165], v[10:13], v[174:177]
	v_mfma_f32_16x16x32_bf16 v[6:9], v[162:165], v[14:17], v[178:181]
	v_mov_b32_e32 v14, v195
	s_barrier
; DI int tidx() { int t = threadIdx.x; asm volatile("" : "+v"(t)); return t; }
; template <int EPI>
; DI void gemm_phase(const P& p, int l, const u16* __restrict__ A, const u16* __restrict__ Bt, int mpx, char* lds) {
;     ...
;   GSTORE(As0, Bs0)
;   const int tid_e = tidx();
;   const int lane = tid_e & 63, w = tid_e >> 6, r = lane & 15, g = lane >> 4, wm = w >> 2, wn = w & 3;
;   if constexpr (EPI == 1) {
;     const float alpha = 1.4142135623730951f;
;     float* Cw = (float*)(lds + 65536) + w * (16 * 68);
;     const int mr = m0 < MLAT ? (m0 >> 11) : 16;
;     const int colw = n0 + wn * 64;
;     const float* gate = p.mod + (size_t)(l * 17 + mr) * 3072 + 2048 + colw;
;     const float* xr = ((l == 0) ? (m0 < MLAT ? p.x + (size_t)m0 * 1024 : p.ctx + (size_t)(m0 - MLAT) * 1024)
;                                 : p.out + (size_t)m0 * 1024) + (size_t)(wm * 128) * 1024 + colw;
;     float* Z = (float*)p.slab + (size_t)(m0 + wm * 128) * 1024 + colw;
;     const int c4 = (lane & 15) * 4, rr0 = lane >> 4;
;     const float4 gt = *(const float4*)(gate + c4);
;     float4 xn[4];
; #pragma unroll
;     for (int i = 0; i < 4; ++i) xn[i] = *(const float4*)(xr + (size_t)(rr0 + 4 * i) * 1024 + c4);
; #pragma unroll
;     for (int mi = 0; mi < 8; ++mi) {
;       float4 xv[4];
; #pragma unroll
;       for (int i = 0; i < 4; ++i) xv[i] = xn[i];
;       if (mi < 7) {
; #pragma unroll
;         for (int i = 0; i < 4; ++i) xn[i] = *(const float4*)(xr + (size_t)((mi + 1) * 16 + rr0 + 4 * i) * 1024 + c4);
;       }
; #pragma unroll
;       for (int ni = 0; ni < 4; ++ni)
; #pragma unroll
;         for (int j = 0; j < 4; ++j) Cw[(g * 4 + j) * 68 + ni * 16 + r] = acc[mi][ni][j];
;       __builtin_amdgcn_fence(__ATOMIC_RELEASE, "wavefront");
; #pragma unroll
;       for (int i = 0; i < 4; ++i) {
;         const int row = rr0 + 4 * i;
;         const float4 a = *(const float4*)&Cw[row * 68 + c4];
;         float4 z;
;         z.x = alpha * xv[i].x + gt.x * a.x;
;         z.y = alpha * xv[i].y + gt.y * a.y;
;         z.z = alpha * xv[i].z + gt.z * a.z;
;         z.w = alpha * xv[i].w + gt.w * a.w;
;         *(float4*)(Z + (size_t)(mi * 16 + row) * 1024 + c4) = z;
	s_waitcnt vmcnt(7)
	ds_write_b128 v198, v[18:21]
	s_waitcnt vmcnt(5)
	ds_write_b128 v198, v[86:89] offset:8192
	s_waitcnt vmcnt(4)
	ds_write_b128 v198, v[90:93] offset:16384
	s_waitcnt vmcnt(3)
	ds_write_b128 v198, v[94:97] offset:24576
	ds_write_b128 v198, v[98:101] offset:32768
	s_waitcnt vmcnt(2)
	ds_write_b128 v198, v[102:105] offset:40960
	s_waitcnt vmcnt(1)
	ds_write_b128 v198, v[106:109] offset:49152
	s_waitcnt vmcnt(0)
	ds_write_b128 v198, v[110:113] offset:57344
	s_movk_i32 s2, 0x1100
	v_lshrrev_b32_e32 v0, 6, v14
	v_mul_lo_u32 v19, v0, s2
	s_min_i32 s2, s60, 0x8000
	s_lshr_b32 s2, s2, 11
	s_mul_i32 s46, s50, 17
	v_and_b32_e32 v0, 0xc0, v14
	s_add_i32 s2, s2, s46
	v_readlane_b32 s64, v255, 28
	v_or_b32_e32 v0, s61, v0
	s_mul_hi_i32 s47, s2, 0x3000
	s_mulk_i32 s2, 0x3000
	v_readlane_b32 s66, v255, 30
	v_readlane_b32 s67, v255, 31
	s_add_u32 s46, s66, s2
	v_lshlrev_b64 v[10:11], 2, v[0:1]
	v_mov_b32_e32 v0, 0x8000
	s_addc_u32 s47, s67, s47
	v_sub_co_u32_e32 v0, vcc, s60, v0
	v_lshl_add_u64 v[12:13], s[46:47], 0, v[10:11]
	s_and_b64 s[46:47], vcc, exec
	v_readfirstlane_b32 s2, v0
	s_cselect_b32 s2, s60, s2
	s_cselect_b32 s48, 0, 16
	s_and_b64 s[46:47], s[0:1], exec
	s_cselect_b32 s46, s48, 0x88
	s_cselect_b32 s2, s2, s60
	s_add_u32 s46, s96, s46
	s_addc_u32 s47, s97, 0
	s_load_dwordx2 s[46:47], s[46:47], 0x0
	v_ashrrev_i32_e32 v0, 1, v14
	v_and_b32_e32 v18, 15, v14
	v_bfe_u32 v88, v14, 4, 2
	s_lshl_b64 s[48:49], s[2:3], 12
	v_and_b32_e32 v14, 0xffffff80, v0
	s_waitcnt lgkmcnt(0)
	s_add_u32 s46, s46, s48
	v_ashrrev_i32_e32 v15, 31, v14
	s_addc_u32 s47, s47, s49
	v_lshlrev_b64 v[16:17], 12, v[14:15]
	v_lshl_add_u64 v[16:17], s[46:47], 0, v[16:17]
	v_add_u32_e32 v14, s60, v14
	v_lshl_add_u64 v[16:17], v[16:17], 0, v[10:11]
	v_ashrrev_i32_e32 v15, 31, v14
	v_lshlrev_b32_e32 v0, 4, v18
	v_lshlrev_b64 v[14:15], 12, v[14:15]
	v_lshlrev_b32_e32 v20, 2, v18
	v_lshl_add_u64 v[16:17], v[16:17], 0, v[0:1]
	v_lshlrev_b32_e32 v86, 12, v88
	v_mov_b32_e32 v87, v1
	v_lshl_add_u64 v[14:15], s[18:19], 0, v[14:15]
	v_lshl_add_u64 v[162:163], v[16:17], 0, v[86:87]
	v_add3_u32 v16, s78, v19, v20
	s_movk_i32 s2, 0x440
	v_lshl_add_u64 v[12:13], v[12:13], 0, v[0:1]
	v_lshl_add_u64 v[10:11], v[14:15], 0, v[10:11]
	v_mad_u32_u24 v165, v88, s2, v16
	s_movk_i32 s2, 0x2000
	v_lshl_add_u64 v[14:15], v[10:11], 0, v[0:1]
	v_add_co_u32_e32 v10, vcc, s2, v12
	ds_write2_b32 v165, v146, v154 offset1:16
	ds_write2_b32 v165, v147, v155 offset0:68 offset1:84
	ds_write2_b32 v165, v148, v156 offset0:136 offset1:152
	ds_write2_b32 v165, v149, v157 offset0:204 offset1:220
	ds_write2_b32 v165, v150, v158 offset0:32 offset1:48
	ds_write2_b32 v165, v151, v159 offset0:100 offset1:116
	ds_write2_b32 v165, v152, v160 offset0:168 offset1:184
	ds_write2_b32 v165, v153, v161 offset0:236 offset1:252
	v_addc_co_u32_e32 v11, vcc, 0, v13, vcc
	v_mad_u32_u24 v17, v18, 12, v16
	global_load_dwordx4 v[18:21], v[10:11], off nt
	s_nop 0
	global_load_dwordx4 v[10:13], v[162:163], off nt
	v_or_b32_e32 v0, 4, v88
	v_add_co_u32_e32 v16, vcc, s94, v162
	v_mad_u32_u24 v164, v88, s79, v17
	v_mad_u32_u24 v158, v0, s79, v17
	v_addc_co_u32_e32 v17, vcc, 0, v163, vcc
	global_load_dwordx4 v[102:105], v[16:17], off nt
	v_add_co_u32_e32 v16, vcc, s21, v162
	v_lshlrev_b32_e32 v0, 12, v0
	s_nop 0
	v_addc_co_u32_e32 v17, vcc, 0, v163, vcc
	global_load_dwordx4 v[94:97], v[16:17], off nt
	v_lshl_add_u64 v[156:157], v[14:15], 0, v[0:1]
	v_or_b32_e32 v0, 0x8000, v86
	v_lshl_add_u64 v[154:155], v[14:15], 0, v[0:1]
	v_or_b32_e32 v0, 0xc000, v86
	s_mov_b32 s2, 0xc000
	v_lshl_add_u64 v[152:153], v[14:15], 0, v[86:87]
	v_lshl_add_u64 v[150:151], v[14:15], 0, v[0:1]
	v_add_co_u32_e32 v14, vcc, s2, v162
	s_mov_b32 s2, 0x14000
	s_nop 0
	v_addc_co_u32_e32 v15, vcc, 0, v163, vcc
	global_load_dwordx4 v[86:89], v[14:15], off nt
	v_add_co_u32_e32 v14, vcc, s85, v162
	s_mov_b32 s46, 0x30000
	s_nop 0
	v_addc_co_u32_e32 v15, vcc, 0, v163, vcc
	global_load_dwordx4 v[146:149], v[14:15], off nt
	v_add_co_u32_e32 v14, vcc, s2, v162
	s_mov_b32 s2, 0x18000
	s_nop 0
	v_addc_co_u32_e32 v15, vcc, 0, v163, vcc
	global_load_dwordx4 v[106:109], v[14:15], off nt
	v_add_co_u32_e32 v14, vcc, s2, v162
	s_mov_b32 s2, 0x1c000
	s_nop 0
	v_addc_co_u32_e32 v15, vcc, 0, v163, vcc
	global_load_dwordx4 v[98:101], v[14:15], off nt
	v_add_co_u32_e32 v14, vcc, s2, v162
	s_mov_b32 s2, 0x24000
	s_nop 0
	v_addc_co_u32_e32 v15, vcc, 0, v163, vcc
	global_load_dwordx4 v[90:93], v[14:15], off nt
	ds_read_b128 v[14:17], v164
	s_mov_b32 s60, s58
	s_mov_b32 s61, s59
	s_mov_b64 s[48:49], s[42:43]
	v_readlane_b32 s65, v255, 29
	v_readlane_b32 s68, v255, 32
	v_readlane_b32 s69, v255, 33
	v_readlane_b32 s70, v255, 34
	v_readlane_b32 s71, v255, 35
	s_waitcnt vmcnt(8) lgkmcnt(0)
	v_pk_mul_f32 v[14:15], v[18:19], v[14:15]
	s_waitcnt vmcnt(7)
	v_pk_fma_f32 v[10:11], v[10:11], s[34:35], v[14:15] op_sel_hi:[1,0,1]
	v_pk_mul_f32 v[14:15], v[20:21], v[16:17]
	s_nop 0
	v_pk_fma_f32 v[12:13], v[12:13], s[34:35], v[14:15] op_sel_hi:[1,0,1]
	global_store_dwordx4 v[152:153], v[10:13], off sc1 nt
	ds_read_b128 v[10:13], v158
	s_waitcnt lgkmcnt(0)
	v_pk_mul_f32 v[10:11], v[18:19], v[10:11]
	v_pk_mul_f32 v[12:13], v[20:21], v[12:13]
	s_waitcnt vmcnt(7)
	v_pk_fma_f32 v[10:11], v[102:103], s[34:35], v[10:11] op_sel_hi:[1,0,1]
	v_pk_fma_f32 v[12:13], v[104:105], s[34:35], v[12:13] op_sel_hi:[1,0,1]
	global_store_dwordx4 v[156:157], v[10:13], off sc1 nt
	ds_read_b128 v[10:13], v158 offset:1088
	s_waitcnt lgkmcnt(0)
	v_pk_mul_f32 v[10:11], v[18:19], v[10:11]
	v_pk_mul_f32 v[12:13], v[20:21], v[12:13]
	s_waitcnt vmcnt(7)
; template <int EPI>
; DI void gemm_phase(const P& p, int l, const u16* __restrict__ A, const u16* __restrict__ Bt, int mpx, char* lds) {
;     ...
;     for (int mi = 0; mi < 8; ++mi) {
;       float4 xv[4];
; #pragma unroll
;       for (int i = 0; i < 4; ++i) xv[i] = xn[i];
;       if (mi < 7) {
; #pragma unroll
;         for (int i = 0; i < 4; ++i) xn[i] = *(const float4*)(xr + (size_t)((mi + 1) * 16 + rr0 + 4 * i) * 1024 + c4);
;       }
; #pragma unroll
;       for (int ni = 0; ni < 4; ++ni)
; #pragma unroll
;         for (int j = 0; j < 4; ++j) Cw[(g * 4 + j) * 68 + ni * 16 + r] = acc[mi][ni][j];
;       __builtin_amdgcn_fence(__ATOMIC_RELEASE, "wavefront");
; #pragma unroll
;       for (int i = 0; i < 4; ++i) {
;         const int row = rr0 + 4 * i;
;         const float4 a = *(const float4*)&Cw[row * 68 + c4];
;         float4 z;
;         z.x = alpha * xv[i].x + gt.x * a.x;
;         z.y = alpha * xv[i].y + gt.y * a.y;
;         z.z = alpha * xv[i].z + gt.z * a.z;
;         z.w = alpha * xv[i].w + gt.w * a.w;
;         *(float4*)(Z + (size_t)(mi * 16 + row) * 1024 + c4) = z;
;       }
;       __builtin_amdgcn_fence(__ATOMIC_RELEASE, "wavefront");
	v_pk_fma_f32 v[10:11], v[94:95], s[34:35], v[10:11] op_sel_hi:[1,0,1]
	v_pk_fma_f32 v[12:13], v[96:97], s[34:35], v[12:13] op_sel_hi:[1,0,1]
	global_store_dwordx4 v[154:155], v[10:13], off sc1 nt
	ds_read_b128 v[10:13], v158 offset:2176
	s_waitcnt lgkmcnt(0)
	v_pk_mul_f32 v[10:11], v[18:19], v[10:11]
	v_pk_mul_f32 v[12:13], v[20:21], v[12:13]
	s_waitcnt vmcnt(7)
	v_pk_fma_f32 v[10:11], v[86:87], s[34:35], v[10:11] op_sel_hi:[1,0,1]
	v_pk_fma_f32 v[12:13], v[88:89], s[34:35], v[12:13] op_sel_hi:[1,0,1]
	global_store_dwordx4 v[150:151], v[10:13], off sc1 nt
	ds_write2_b32 v165, v138, v142 offset1:16
	ds_write2_b32 v165, v139, v143 offset0:68 offset1:84
	ds_write2_b32 v165, v140, v144 offset0:136 offset1:152
	ds_write2_b32 v165, v141, v145 offset0:204 offset1:220
	ds_write2_b32 v165, v130, v134 offset0:32 offset1:48
	ds_write2_b32 v165, v131, v135 offset0:100 offset1:116
	ds_write2_b32 v165, v132, v136 offset0:168 offset1:184
	ds_write2_b32 v165, v133, v137 offset0:236 offset1:252
	v_add_co_u32_e32 v10, vcc, s33, v162
	s_nop 1
	v_addc_co_u32_e32 v11, vcc, 0, v163, vcc
	global_load_dwordx4 v[110:113], v[10:11], off nt
	v_add_co_u32_e32 v10, vcc, s2, v162
	s_mov_b32 s2, 0x28000
	s_nop 0
	v_addc_co_u32_e32 v11, vcc, 0, v163, vcc
	global_load_dwordx4 v[102:105], v[10:11], off nt
	v_add_co_u32_e32 v10, vcc, s2, v162
	s_mov_b32 s2, 0x2c000
	s_nop 0
	v_addc_co_u32_e32 v11, vcc, 0, v163, vcc
	global_load_dwordx4 v[94:97], v[10:11], off nt
	v_add_co_u32_e32 v10, vcc, s2, v162
	s_mov_b32 s2, 0x34000
	s_nop 0
	v_addc_co_u32_e32 v11, vcc, 0, v163, vcc
	global_load_dwordx4 v[86:89], v[10:11], off nt
	ds_read_b128 v[10:13], v164
	v_add_co_u32_e32 v14, vcc, s85, v152
	s_waitcnt lgkmcnt(0)
	v_pk_mul_f32 v[10:11], v[18:19], v[10:11]
	v_pk_mul_f32 v[12:13], v[20:21], v[12:13]
	s_waitcnt vmcnt(11)
	v_pk_fma_f32 v[10:11], v[146:147], s[34:35], v[10:11] op_sel_hi:[1,0,1]
	v_pk_fma_f32 v[12:13], v[148:149], s[34:35], v[12:13] op_sel_hi:[1,0,1]
	v_addc_co_u32_e32 v15, vcc, 0, v153, vcc
	global_store_dwordx4 v[14:15], v[10:13], off sc1 nt
	ds_read_b128 v[10:13], v158
	v_add_co_u32_e32 v14, vcc, s85, v156
	s_waitcnt lgkmcnt(0)
	v_pk_mul_f32 v[10:11], v[18:19], v[10:11]
	v_pk_mul_f32 v[12:13], v[20:21], v[12:13]
	s_waitcnt vmcnt(11)
	v_pk_fma_f32 v[10:11], v[106:107], s[34:35], v[10:11] op_sel_hi:[1,0,1]
	v_pk_fma_f32 v[12:13], v[108:109], s[34:35], v[12:13] op_sel_hi:[1,0,1]
	v_addc_co_u32_e32 v15, vcc, 0, v157, vcc
	global_store_dwordx4 v[14:15], v[10:13], off sc1 nt
	ds_read_b128 v[10:13], v158 offset:1088
	v_add_co_u32_e32 v14, vcc, s85, v154
	s_waitcnt lgkmcnt(0)
	v_pk_mul_f32 v[10:11], v[18:19], v[10:11]
	v_pk_mul_f32 v[12:13], v[20:21], v[12:13]
	s_waitcnt vmcnt(11)
	v_pk_fma_f32 v[10:11], v[98:99], s[34:35], v[10:11] op_sel_hi:[1,0,1]
	v_pk_fma_f32 v[12:13], v[100:101], s[34:35], v[12:13] op_sel_hi:[1,0,1]
	v_addc_co_u32_e32 v15, vcc, 0, v155, vcc
	global_store_dwordx4 v[14:15], v[10:13], off sc1 nt
	ds_read_b128 v[10:13], v158 offset:2176
	v_add_co_u32_e32 v14, vcc, s85, v150
	s_waitcnt lgkmcnt(0)
	v_pk_mul_f32 v[10:11], v[18:19], v[10:11]
	v_pk_mul_f32 v[12:13], v[20:21], v[12:13]
	s_waitcnt vmcnt(11)
	v_pk_fma_f32 v[10:11], v[90:91], s[34:35], v[10:11] op_sel_hi:[1,0,1]
	v_pk_fma_f32 v[12:13], v[92:93], s[34:35], v[12:13] op_sel_hi:[1,0,1]
	v_addc_co_u32_e32 v15, vcc, 0, v151, vcc
	global_store_dwordx4 v[14:15], v[10:13], off sc1 nt
	ds_write2_b32 v165, v122, v126 offset1:16
	ds_write2_b32 v165, v123, v127 offset0:68 offset1:84
	ds_write2_b32 v165, v124, v128 offset0:136 offset1:152
	ds_write2_b32 v165, v125, v129 offset0:204 offset1:220
	ds_write2_b32 v165, v114, v118 offset0:32 offset1:48
	ds_write2_b32 v165, v115, v119 offset0:100 offset1:116
	ds_write2_b32 v165, v116, v120 offset0:168 offset1:184
	ds_write2_b32 v165, v117, v121 offset0:236 offset1:252
	v_add_co_u32_e32 v10, vcc, s46, v162
	s_nop 1
	v_addc_co_u32_e32 v11, vcc, 0, v163, vcc
	global_load_dwordx4 v[114:117], v[10:11], off nt
	v_add_co_u32_e32 v10, vcc, s2, v162
	s_mov_b32 s2, 0x38000
	s_nop 0
	v_addc_co_u32_e32 v11, vcc, 0, v163, vcc
	global_load_dwordx4 v[106:109], v[10:11], off nt
	v_add_co_u32_e32 v10, vcc, s2, v162
	s_mov_b32 s2, 0x3c000
	s_nop 0
	v_addc_co_u32_e32 v11, vcc, 0, v163, vcc
	global_load_dwordx4 v[98:101], v[10:11], off nt
	v_add_co_u32_e32 v10, vcc, s2, v162
	s_mov_b32 s2, 0x44000
	s_nop 0
	v_addc_co_u32_e32 v11, vcc, 0, v163, vcc
	global_load_dwordx4 v[90:93], v[10:11], off nt
	ds_read_b128 v[10:13], v164
	v_add_co_u32_e32 v14, vcc, s33, v152
	s_waitcnt lgkmcnt(0)
	v_pk_mul_f32 v[10:11], v[18:19], v[10:11]
	v_pk_mul_f32 v[12:13], v[20:21], v[12:13]
	s_waitcnt vmcnt(11)
	v_pk_fma_f32 v[10:11], v[110:111], s[34:35], v[10:11] op_sel_hi:[1,0,1]
	v_pk_fma_f32 v[12:13], v[112:113], s[34:35], v[12:13] op_sel_hi:[1,0,1]
	v_addc_co_u32_e32 v15, vcc, 0, v153, vcc
	global_store_dwordx4 v[14:15], v[10:13], off sc1 nt
	ds_read_b128 v[10:13], v158
	v_add_co_u32_e32 v14, vcc, s33, v156
	s_waitcnt lgkmcnt(0)
	v_pk_mul_f32 v[10:11], v[18:19], v[10:11]
	v_pk_mul_f32 v[12:13], v[20:21], v[12:13]
	s_waitcnt vmcnt(11)
	v_pk_fma_f32 v[10:11], v[102:103], s[34:35], v[10:11] op_sel_hi:[1,0,1]
	v_pk_fma_f32 v[12:13], v[104:105], s[34:35], v[12:13] op_sel_hi:[1,0,1]
	v_addc_co_u32_e32 v15, vcc, 0, v157, vcc
	global_store_dwordx4 v[14:15], v[10:13], off sc1 nt
	ds_read_b128 v[10:13], v158 offset:1088
	v_add_co_u32_e32 v14, vcc, s33, v154
	s_waitcnt lgkmcnt(0)
	v_pk_mul_f32 v[10:11], v[18:19], v[10:11]
	v_pk_mul_f32 v[12:13], v[20:21], v[12:13]
	s_waitcnt vmcnt(11)
; template <int EPI>
; DI void gemm_phase(const P& p, int l, const u16* __restrict__ A, const u16* __restrict__ Bt, int mpx, char* lds) {
;     ...
;     for (int mi = 0; mi < 8; ++mi) {
;       float4 xv[4];
; #pragma unroll
;       for (int i = 0; i < 4; ++i) xv[i] = xn[i];
;       if (mi < 7) {
; #pragma unroll
;         for (int i = 0; i < 4; ++i) xn[i] = *(const float4*)(xr + (size_t)((mi + 1) * 16 + rr0 + 4 * i) * 1024 + c4);
;       }
; #pragma unroll
;       for (int ni = 0; ni < 4; ++ni)
; #pragma unroll
;         for (int j = 0; j < 4; ++j) Cw[(g * 4 + j) * 68 + ni * 16 + r] = acc[mi][ni][j];
;       __builtin_amdgcn_fence(__ATOMIC_RELEASE, "wavefront");
; #pragma unroll
;       for (int i = 0; i < 4; ++i) {
;         const int row = rr0 + 4 * i;
;         const float4 a = *(const float4*)&Cw[row * 68 + c4];
;         float4 z;
;         z.x = alpha * xv[i].x + gt.x * a.x;
;         z.y = alpha * xv[i].y + gt.y * a.y;
;         z.z = alpha * xv[i].z + gt.z * a.z;
;         z.w = alpha * xv[i].w + gt.w * a.w;
;         *(float4*)(Z + (size_t)(mi * 16 + row) * 1024 + c4) = z;
;       }
;       __builtin_amdgcn_fence(__ATOMIC_RELEASE, "wavefront");
	v_pk_fma_f32 v[10:11], v[94:95], s[34:35], v[10:11] op_sel_hi:[1,0,1]
	v_pk_fma_f32 v[12:13], v[96:97], s[34:35], v[12:13] op_sel_hi:[1,0,1]
	v_addc_co_u32_e32 v15, vcc, 0, v155, vcc
	global_store_dwordx4 v[14:15], v[10:13], off sc1 nt
	ds_read_b128 v[10:13], v158 offset:2176
	v_add_co_u32_e32 v14, vcc, s33, v150
	s_waitcnt lgkmcnt(0)
	v_pk_mul_f32 v[10:11], v[18:19], v[10:11]
	v_pk_mul_f32 v[12:13], v[20:21], v[12:13]
	s_waitcnt vmcnt(11)
	v_pk_fma_f32 v[10:11], v[86:87], s[34:35], v[10:11] op_sel_hi:[1,0,1]
	v_pk_fma_f32 v[12:13], v[88:89], s[34:35], v[12:13] op_sel_hi:[1,0,1]
	v_addc_co_u32_e32 v15, vcc, 0, v151, vcc
	global_store_dwordx4 v[14:15], v[10:13], off sc1 nt
	ds_write2_b32 v165, v78, v82 offset1:16
	ds_write2_b32 v165, v79, v83 offset0:68 offset1:84
	ds_write2_b32 v165, v80, v84 offset0:136 offset1:152
	ds_write2_b32 v165, v81, v85 offset0:204 offset1:220
	ds_write2_b32 v165, v70, v74 offset0:32 offset1:48
	ds_write2_b32 v165, v71, v75 offset0:100 offset1:116
	ds_write2_b32 v165, v72, v76 offset0:168 offset1:184
	ds_write2_b32 v165, v73, v77 offset0:236 offset1:252
	v_add_co_u32_e32 v10, vcc, s35, v162
	s_nop 1
	v_addc_co_u32_e32 v11, vcc, 0, v163, vcc
	global_load_dwordx4 v[82:85], v[10:11], off nt
	v_add_co_u32_e32 v10, vcc, s2, v162
	s_mov_b32 s2, 0x48000
	s_nop 0
	v_addc_co_u32_e32 v11, vcc, 0, v163, vcc
	global_load_dwordx4 v[78:81], v[10:11], off nt
	v_add_co_u32_e32 v10, vcc, s2, v162
	s_mov_b32 s2, 0x4c000
	s_nop 0
	v_addc_co_u32_e32 v11, vcc, 0, v163, vcc
	global_load_dwordx4 v[74:77], v[10:11], off nt
	v_add_co_u32_e32 v10, vcc, s2, v162
	s_mov_b32 s2, 0x54000
	s_nop 0
	v_addc_co_u32_e32 v11, vcc, 0, v163, vcc
	global_load_dwordx4 v[70:73], v[10:11], off nt
	ds_read_b128 v[10:13], v164
	v_add_co_u32_e32 v14, vcc, s46, v152
	s_waitcnt lgkmcnt(0)
	v_pk_mul_f32 v[10:11], v[18:19], v[10:11]
	v_pk_mul_f32 v[12:13], v[20:21], v[12:13]
	s_waitcnt vmcnt(11)
	v_pk_fma_f32 v[10:11], v[114:115], s[34:35], v[10:11] op_sel_hi:[1,0,1]
	v_pk_fma_f32 v[12:13], v[116:117], s[34:35], v[12:13] op_sel_hi:[1,0,1]
	v_addc_co_u32_e32 v15, vcc, 0, v153, vcc
	global_store_dwordx4 v[14:15], v[10:13], off sc1 nt
	ds_read_b128 v[10:13], v158
	v_add_co_u32_e32 v14, vcc, s46, v156
	s_waitcnt lgkmcnt(0)
	v_pk_mul_f32 v[10:11], v[18:19], v[10:11]
	v_pk_mul_f32 v[12:13], v[20:21], v[12:13]
	s_waitcnt vmcnt(11)
	v_pk_fma_f32 v[10:11], v[106:107], s[34:35], v[10:11] op_sel_hi:[1,0,1]
	v_pk_fma_f32 v[12:13], v[108:109], s[34:35], v[12:13] op_sel_hi:[1,0,1]
	v_addc_co_u32_e32 v15, vcc, 0, v157, vcc
	global_store_dwordx4 v[14:15], v[10:13], off sc1 nt
	ds_read_b128 v[10:13], v158 offset:1088
	v_add_co_u32_e32 v14, vcc, s46, v154
	s_waitcnt lgkmcnt(0)
	v_pk_mul_f32 v[10:11], v[18:19], v[10:11]
	v_pk_mul_f32 v[12:13], v[20:21], v[12:13]
	s_waitcnt vmcnt(11)
	v_pk_fma_f32 v[10:11], v[98:99], s[34:35], v[10:11] op_sel_hi:[1,0,1]
	v_pk_fma_f32 v[12:13], v[100:101], s[34:35], v[12:13] op_sel_hi:[1,0,1]
	v_addc_co_u32_e32 v15, vcc, 0, v155, vcc
	global_store_dwordx4 v[14:15], v[10:13], off sc1 nt
	ds_read_b128 v[10:13], v158 offset:2176
	v_add_co_u32_e32 v14, vcc, s46, v150
	s_mov_b32 s46, 0x50000
	s_nop 0
	v_addc_co_u32_e32 v15, vcc, 0, v151, vcc
	s_waitcnt lgkmcnt(0)
	v_pk_mul_f32 v[10:11], v[18:19], v[10:11]
	v_pk_mul_f32 v[12:13], v[20:21], v[12:13]
	s_waitcnt vmcnt(11)
	v_pk_fma_f32 v[10:11], v[90:91], s[34:35], v[10:11] op_sel_hi:[1,0,1]
	v_pk_fma_f32 v[12:13], v[92:93], s[34:35], v[12:13] op_sel_hi:[1,0,1]
	global_store_dwordx4 v[14:15], v[10:13], off sc1 nt
	ds_write2_b32 v165, v62, v66 offset1:16
	ds_write2_b32 v165, v63, v67 offset0:68 offset1:84
	ds_write2_b32 v165, v64, v68 offset0:136 offset1:152
	ds_write2_b32 v165, v65, v69 offset0:204 offset1:220
	ds_write2_b32 v165, v54, v58 offset0:32 offset1:48
	ds_write2_b32 v165, v55, v59 offset0:100 offset1:116
	ds_write2_b32 v165, v56, v60 offset0:168 offset1:184
	ds_write2_b32 v165, v57, v61 offset0:236 offset1:252
	v_add_co_u32_e32 v10, vcc, s46, v162
	s_nop 1
	v_addc_co_u32_e32 v11, vcc, 0, v163, vcc
	global_load_dwordx4 v[66:69], v[10:11], off nt
	v_add_co_u32_e32 v10, vcc, s2, v162
	s_mov_b32 s2, 0x58000
	s_nop 0
	v_addc_co_u32_e32 v11, vcc, 0, v163, vcc
	global_load_dwordx4 v[62:65], v[10:11], off nt
	v_add_co_u32_e32 v10, vcc, s2, v162
	s_mov_b32 s2, 0x5c000
	s_nop 0
	v_addc_co_u32_e32 v11, vcc, 0, v163, vcc
	global_load_dwordx4 v[58:61], v[10:11], off nt
	v_add_co_u32_e32 v10, vcc, s2, v162
	s_mov_b32 s2, 0x64000
	s_nop 0
	v_addc_co_u32_e32 v11, vcc, 0, v163, vcc
	global_load_dwordx4 v[54:57], v[10:11], off nt
	ds_read_b128 v[10:13], v164
	v_add_co_u32_e32 v14, vcc, s35, v152
	s_waitcnt lgkmcnt(0)
	v_pk_mul_f32 v[10:11], v[18:19], v[10:11]
	v_pk_mul_f32 v[12:13], v[20:21], v[12:13]
	s_waitcnt vmcnt(11)
	v_pk_fma_f32 v[10:11], v[82:83], s[34:35], v[10:11] op_sel_hi:[1,0,1]
	v_pk_fma_f32 v[12:13], v[84:85], s[34:35], v[12:13] op_sel_hi:[1,0,1]
	v_addc_co_u32_e32 v15, vcc, 0, v153, vcc
	global_store_dwordx4 v[14:15], v[10:13], off sc1 nt
	ds_read_b128 v[10:13], v158
	v_add_co_u32_e32 v14, vcc, s35, v156
	s_waitcnt lgkmcnt(0)
	v_pk_mul_f32 v[10:11], v[18:19], v[10:11]
	v_pk_mul_f32 v[12:13], v[20:21], v[12:13]
	s_waitcnt vmcnt(11)
	v_pk_fma_f32 v[10:11], v[78:79], s[34:35], v[10:11] op_sel_hi:[1,0,1]
	v_pk_fma_f32 v[12:13], v[80:81], s[34:35], v[12:13] op_sel_hi:[1,0,1]
	v_addc_co_u32_e32 v15, vcc, 0, v157, vcc
	global_store_dwordx4 v[14:15], v[10:13], off sc1 nt
	ds_read_b128 v[10:13], v158 offset:1088
	v_add_co_u32_e32 v14, vcc, s35, v154
	s_waitcnt lgkmcnt(0)
	v_pk_mul_f32 v[10:11], v[18:19], v[10:11]
	v_pk_mul_f32 v[12:13], v[20:21], v[12:13]
	s_waitcnt vmcnt(11)
; template <int EPI>
; DI void gemm_phase(const P& p, int l, const u16* __restrict__ A, const u16* __restrict__ Bt, int mpx, char* lds) {
;     ...
;     for (int mi = 0; mi < 8; ++mi) {
;       float4 xv[4];
; #pragma unroll
;       for (int i = 0; i < 4; ++i) xv[i] = xn[i];
;       if (mi < 7) {
; #pragma unroll
;         for (int i = 0; i < 4; ++i) xn[i] = *(const float4*)(xr + (size_t)((mi + 1) * 16 + rr0 + 4 * i) * 1024 + c4);
;       }
; #pragma unroll
;       for (int ni = 0; ni < 4; ++ni)
; #pragma unroll
;         for (int j = 0; j < 4; ++j) Cw[(g * 4 + j) * 68 + ni * 16 + r] = acc[mi][ni][j];
;       __builtin_amdgcn_fence(__ATOMIC_RELEASE, "wavefront");
; #pragma unroll
;       for (int i = 0; i < 4; ++i) {
;         const int row = rr0 + 4 * i;
;         const float4 a = *(const float4*)&Cw[row * 68 + c4];
;         float4 z;
;         z.x = alpha * xv[i].x + gt.x * a.x;
;         z.y = alpha * xv[i].y + gt.y * a.y;
;         z.z = alpha * xv[i].z + gt.z * a.z;
;         z.w = alpha * xv[i].w + gt.w * a.w;
;         *(float4*)(Z + (size_t)(mi * 16 + row) * 1024 + c4) = z;
;       }
;       __builtin_amdgcn_fence(__ATOMIC_RELEASE, "wavefront");
	v_pk_fma_f32 v[10:11], v[74:75], s[34:35], v[10:11] op_sel_hi:[1,0,1]
	v_pk_fma_f32 v[12:13], v[76:77], s[34:35], v[12:13] op_sel_hi:[1,0,1]
	v_addc_co_u32_e32 v15, vcc, 0, v155, vcc
	global_store_dwordx4 v[14:15], v[10:13], off sc1 nt
	ds_read_b128 v[10:13], v158 offset:2176
	v_add_co_u32_e32 v14, vcc, s35, v150
	s_waitcnt lgkmcnt(0)
	v_pk_mul_f32 v[10:11], v[18:19], v[10:11]
	v_pk_mul_f32 v[12:13], v[20:21], v[12:13]
	s_waitcnt vmcnt(11)
	v_pk_fma_f32 v[10:11], v[70:71], s[34:35], v[10:11] op_sel_hi:[1,0,1]
	v_pk_fma_f32 v[12:13], v[72:73], s[34:35], v[12:13] op_sel_hi:[1,0,1]
	v_addc_co_u32_e32 v15, vcc, 0, v151, vcc
	global_store_dwordx4 v[14:15], v[10:13], off sc1 nt
	ds_write2_b32 v165, v46, v50 offset1:16
	ds_write2_b32 v165, v47, v51 offset0:68 offset1:84
	ds_write2_b32 v165, v48, v52 offset0:136 offset1:152
	ds_write2_b32 v165, v49, v53 offset0:204 offset1:220
	ds_write2_b32 v165, v38, v42 offset0:32 offset1:48
	ds_write2_b32 v165, v39, v43 offset0:100 offset1:116
	ds_write2_b32 v165, v40, v44 offset0:168 offset1:184
	ds_write2_b32 v165, v41, v45 offset0:236 offset1:252
	v_add_co_u32_e32 v10, vcc, s39, v162
	s_nop 1
	v_addc_co_u32_e32 v11, vcc, 0, v163, vcc
	global_load_dwordx4 v[50:53], v[10:11], off nt
	v_add_co_u32_e32 v10, vcc, s2, v162
	s_mov_b32 s2, 0x68000
	s_nop 0
	v_addc_co_u32_e32 v11, vcc, 0, v163, vcc
	global_load_dwordx4 v[46:49], v[10:11], off nt
	v_add_co_u32_e32 v10, vcc, s2, v162
	s_mov_b32 s2, 0x6c000
	s_nop 0
	v_addc_co_u32_e32 v11, vcc, 0, v163, vcc
	global_load_dwordx4 v[42:45], v[10:11], off nt
	v_add_co_u32_e32 v10, vcc, s2, v162
	s_mov_b32 s2, 0x74000
	s_nop 0
	v_addc_co_u32_e32 v11, vcc, 0, v163, vcc
	global_load_dwordx4 v[38:41], v[10:11], off nt
	ds_read_b128 v[10:13], v164
	v_add_co_u32_e32 v14, vcc, s46, v152
	s_waitcnt lgkmcnt(0)
	v_pk_mul_f32 v[10:11], v[18:19], v[10:11]
	v_pk_mul_f32 v[12:13], v[20:21], v[12:13]
	s_waitcnt vmcnt(11)
	v_pk_fma_f32 v[10:11], v[66:67], s[34:35], v[10:11] op_sel_hi:[1,0,1]
	v_pk_fma_f32 v[12:13], v[68:69], s[34:35], v[12:13] op_sel_hi:[1,0,1]
	v_addc_co_u32_e32 v15, vcc, 0, v153, vcc
	global_store_dwordx4 v[14:15], v[10:13], off sc1 nt
	ds_read_b128 v[10:13], v158
	v_add_co_u32_e32 v14, vcc, s46, v156
	s_waitcnt lgkmcnt(0)
	v_pk_mul_f32 v[10:11], v[18:19], v[10:11]
	v_pk_mul_f32 v[12:13], v[20:21], v[12:13]
	s_waitcnt vmcnt(11)
	v_pk_fma_f32 v[10:11], v[62:63], s[34:35], v[10:11] op_sel_hi:[1,0,1]
	v_pk_fma_f32 v[12:13], v[64:65], s[34:35], v[12:13] op_sel_hi:[1,0,1]
	v_addc_co_u32_e32 v15, vcc, 0, v157, vcc
	global_store_dwordx4 v[14:15], v[10:13], off sc1 nt
	ds_read_b128 v[10:13], v158 offset:1088
	v_add_co_u32_e32 v14, vcc, s46, v154
	s_waitcnt lgkmcnt(0)
	v_pk_mul_f32 v[10:11], v[18:19], v[10:11]
	v_pk_mul_f32 v[12:13], v[20:21], v[12:13]
	s_waitcnt vmcnt(11)
	v_pk_fma_f32 v[10:11], v[58:59], s[34:35], v[10:11] op_sel_hi:[1,0,1]
	v_pk_fma_f32 v[12:13], v[60:61], s[34:35], v[12:13] op_sel_hi:[1,0,1]
	v_addc_co_u32_e32 v15, vcc, 0, v155, vcc
	global_store_dwordx4 v[14:15], v[10:13], off sc1 nt
	ds_read_b128 v[10:13], v158 offset:2176
	v_add_co_u32_e32 v14, vcc, s46, v150
	s_mov_b32 s46, 0x70000
	s_nop 0
	v_addc_co_u32_e32 v15, vcc, 0, v151, vcc
	s_waitcnt lgkmcnt(0)
	v_pk_mul_f32 v[10:11], v[18:19], v[10:11]
	v_pk_mul_f32 v[12:13], v[20:21], v[12:13]
	s_waitcnt vmcnt(11)
	v_pk_fma_f32 v[10:11], v[54:55], s[34:35], v[10:11] op_sel_hi:[1,0,1]
	v_pk_fma_f32 v[12:13], v[56:57], s[34:35], v[12:13] op_sel_hi:[1,0,1]
	global_store_dwordx4 v[14:15], v[10:13], off sc1 nt
	ds_write2_b32 v165, v30, v34 offset1:16
	ds_write2_b32 v165, v31, v35 offset0:68 offset1:84
	ds_write2_b32 v165, v32, v36 offset0:136 offset1:152
	ds_write2_b32 v165, v33, v37 offset0:204 offset1:220
	ds_write2_b32 v165, v22, v26 offset0:32 offset1:48
	ds_write2_b32 v165, v23, v27 offset0:100 offset1:116
	ds_write2_b32 v165, v24, v28 offset0:168 offset1:184
	ds_write2_b32 v165, v25, v29 offset0:236 offset1:252
	v_add_co_u32_e32 v10, vcc, s46, v162
	s_nop 1
	v_addc_co_u32_e32 v11, vcc, 0, v163, vcc
	global_load_dwordx4 v[10:13], v[10:11], off nt
	v_add_co_u32_e32 v14, vcc, s2, v162
	s_mov_b32 s2, 0x78000
	s_nop 0
	v_addc_co_u32_e32 v15, vcc, 0, v163, vcc
	global_load_dwordx4 v[30:33], v[14:15], off nt
	v_add_co_u32_e32 v14, vcc, s2, v162
	s_mov_b32 s2, 0x7c000
	s_nop 0
	v_addc_co_u32_e32 v15, vcc, 0, v163, vcc
	global_load_dwordx4 v[26:29], v[14:15], off nt
	v_add_co_u32_e32 v14, vcc, s2, v162
	s_nop 1
	v_addc_co_u32_e32 v15, vcc, 0, v163, vcc
	global_load_dwordx4 v[22:25], v[14:15], off nt
	ds_read_b128 v[14:17], v164
	v_add_co_u32_e32 v34, vcc, s39, v152
	s_waitcnt lgkmcnt(0)
; template <int EPI>
; DI void gemm_phase(const P& p, int l, const u16* __restrict__ A, const u16* __restrict__ Bt, int mpx, char* lds) {
;     ...
;     for (int mi = 0; mi < 8; ++mi) {
;       float4 xv[4];
; #pragma unroll
;       for (int i = 0; i < 4; ++i) xv[i] = xn[i];
;       if (mi < 7) {
; #pragma unroll
;         for (int i = 0; i < 4; ++i) xn[i] = *(const float4*)(xr + (size_t)((mi + 1) * 16 + rr0 + 4 * i) * 1024 + c4);
;       }
; #pragma unroll
;       for (int ni = 0; ni < 4; ++ni)
; #pragma unroll
;         for (int j = 0; j < 4; ++j) Cw[(g * 4 + j) * 68 + ni * 16 + r] = acc[mi][ni][j];
;       __builtin_amdgcn_fence(__ATOMIC_RELEASE, "wavefront");
; #pragma unroll
;       for (int i = 0; i < 4; ++i) {
;         const int row = rr0 + 4 * i;
;         const float4 a = *(const float4*)&Cw[row * 68 + c4];
;         float4 z;
;         z.x = alpha * xv[i].x + gt.x * a.x;
;         z.y = alpha * xv[i].y + gt.y * a.y;
;         z.z = alpha * xv[i].z + gt.z * a.z;
;         z.w = alpha * xv[i].w + gt.w * a.w;
;         *(float4*)(Z + (size_t)(mi * 16 + row) * 1024 + c4) = z;
;       }
;       __builtin_amdgcn_fence(__ATOMIC_RELEASE, "wavefront");
;     ...
;   if (!has_next) break;
;   t = tn; m0 = m1; n0 = n1; Ag = Agn; Bg = Bgn;
	v_pk_mul_f32 v[14:15], v[18:19], v[14:15]
	v_pk_mul_f32 v[16:17], v[20:21], v[16:17]
	s_waitcnt vmcnt(11)
	v_pk_fma_f32 v[14:15], v[50:51], s[34:35], v[14:15] op_sel_hi:[1,0,1]
	v_pk_fma_f32 v[16:17], v[52:53], s[34:35], v[16:17] op_sel_hi:[1,0,1]
	v_addc_co_u32_e32 v35, vcc, 0, v153, vcc
	global_store_dwordx4 v[34:35], v[14:17], off sc1 nt
	ds_read_b128 v[14:17], v158
	v_add_co_u32_e32 v34, vcc, s39, v156
	s_waitcnt lgkmcnt(0)
	v_pk_mul_f32 v[14:15], v[18:19], v[14:15]
	v_pk_mul_f32 v[16:17], v[20:21], v[16:17]
	s_waitcnt vmcnt(11)
	v_pk_fma_f32 v[14:15], v[46:47], s[34:35], v[14:15] op_sel_hi:[1,0,1]
	v_pk_fma_f32 v[16:17], v[48:49], s[34:35], v[16:17] op_sel_hi:[1,0,1]
	v_addc_co_u32_e32 v35, vcc, 0, v157, vcc
	global_store_dwordx4 v[34:35], v[14:17], off sc1 nt
	ds_read_b128 v[14:17], v158 offset:1088
	v_add_co_u32_e32 v34, vcc, s39, v154
	s_waitcnt lgkmcnt(0)
	v_pk_mul_f32 v[14:15], v[18:19], v[14:15]
	v_pk_mul_f32 v[16:17], v[20:21], v[16:17]
	s_waitcnt vmcnt(11)
	v_pk_fma_f32 v[14:15], v[42:43], s[34:35], v[14:15] op_sel_hi:[1,0,1]
	v_pk_fma_f32 v[16:17], v[44:45], s[34:35], v[16:17] op_sel_hi:[1,0,1]
	v_addc_co_u32_e32 v35, vcc, 0, v155, vcc
	global_store_dwordx4 v[34:35], v[14:17], off sc1 nt
	ds_read_b128 v[14:17], v158 offset:2176
	v_add_co_u32_e32 v34, vcc, s39, v150
	s_waitcnt lgkmcnt(0)
	v_pk_mul_f32 v[14:15], v[18:19], v[14:15]
	v_pk_mul_f32 v[16:17], v[20:21], v[16:17]
	s_waitcnt vmcnt(11)
	v_pk_fma_f32 v[14:15], v[38:39], s[34:35], v[14:15] op_sel_hi:[1,0,1]
	v_pk_fma_f32 v[16:17], v[40:41], s[34:35], v[16:17] op_sel_hi:[1,0,1]
	v_addc_co_u32_e32 v35, vcc, 0, v151, vcc
	global_store_dwordx4 v[34:35], v[14:17], off sc1 nt
	ds_write2_b32 v165, v166, v170 offset1:16
	ds_write2_b32 v165, v167, v171 offset0:68 offset1:84
	ds_write2_b32 v165, v168, v172 offset0:136 offset1:152
	ds_write2_b32 v165, v169, v173 offset0:204 offset1:220
	ds_write2_b32 v165, v2, v6 offset0:32 offset1:48
	ds_write2_b32 v165, v3, v7 offset0:100 offset1:116
	ds_write2_b32 v165, v4, v8 offset0:168 offset1:184
	ds_write2_b32 v165, v5, v9 offset0:236 offset1:252
	ds_read_b128 v[2:5], v164
	v_add_co_u32_e32 v6, vcc, s46, v152
	s_waitcnt lgkmcnt(0)
	v_pk_mul_f32 v[2:3], v[18:19], v[2:3]
	v_pk_mul_f32 v[4:5], v[20:21], v[4:5]
	v_addc_co_u32_e32 v7, vcc, 0, v153, vcc
	s_waitcnt vmcnt(7)
	v_pk_fma_f32 v[2:3], v[10:11], s[34:35], v[2:3] op_sel_hi:[1,0,1]
	v_pk_fma_f32 v[4:5], v[12:13], s[34:35], v[4:5] op_sel_hi:[1,0,1]
	global_store_dwordx4 v[6:7], v[2:5], off sc1 nt
	ds_read_b128 v[2:5], v158
	v_add_co_u32_e32 v6, vcc, s46, v156
	s_waitcnt lgkmcnt(0)
	v_pk_mul_f32 v[2:3], v[18:19], v[2:3]
	v_pk_mul_f32 v[4:5], v[20:21], v[4:5]
	s_waitcnt vmcnt(7)
	v_pk_fma_f32 v[2:3], v[30:31], s[34:35], v[2:3] op_sel_hi:[1,0,1]
	v_pk_fma_f32 v[4:5], v[32:33], s[34:35], v[4:5] op_sel_hi:[1,0,1]
	v_addc_co_u32_e32 v7, vcc, 0, v157, vcc
	global_store_dwordx4 v[6:7], v[2:5], off sc1 nt
	ds_read_b128 v[2:5], v158 offset:1088
	v_add_co_u32_e32 v6, vcc, s46, v154
	s_mov_b64 s[46:47], s[44:45]
	s_nop 0
	v_addc_co_u32_e32 v7, vcc, 0, v155, vcc
	s_waitcnt lgkmcnt(0)
	v_pk_mul_f32 v[2:3], v[18:19], v[2:3]
	v_pk_mul_f32 v[4:5], v[20:21], v[4:5]
	s_waitcnt vmcnt(7)
	v_pk_fma_f32 v[2:3], v[26:27], s[34:35], v[2:3] op_sel_hi:[1,0,1]
	v_pk_fma_f32 v[4:5], v[28:29], s[34:35], v[4:5] op_sel_hi:[1,0,1]
	global_store_dwordx4 v[6:7], v[2:5], off sc1 nt
	ds_read_b128 v[2:5], v158 offset:2176
	v_add_co_u32_e32 v6, vcc, 0x70000, v150
	s_waitcnt lgkmcnt(0)
	v_pk_mul_f32 v[2:3], v[18:19], v[2:3]
	v_pk_mul_f32 v[4:5], v[20:21], v[4:5]
	v_addc_co_u32_e32 v7, vcc, 0, v151, vcc
	s_waitcnt vmcnt(7)
	v_pk_fma_f32 v[2:3], v[22:23], s[34:35], v[2:3] op_sel_hi:[1,0,1]
	v_pk_fma_f32 v[4:5], v[24:25], s[34:35], v[4:5] op_sel_hi:[1,0,1]
	s_and_b64 vcc, exec, s[40:41]
	global_store_dwordx4 v[6:7], v[2:5], off sc1 nt
	s_cbranch_vccz .LBB0_69
	v_mov_b32_e32 v236, 0x358637bd
